# natten step loop: the step-top wait no longer drains the previous step's two output stores (vmcnt(2) at the top, vmcnt(0) once in the loop preheader)
# speedup vs baseline: 1.0131x; 1.0131x over previous
.LBB0_469:
	s_or_b64 exec, exec, s[48:49]
	s_lshr_b32 s48, s28, 1
	v_cndmask_b32_e64 v24, 0, 1, s[12:13]
	s_and_b32 s69, s48, 15
	v_readfirstlane_b32 s48, v24
	s_lshl_b32 s48, s48, 5
	v_readlane_b32 s6, v253, 2
	s_add_i32 s35, s35, s4
	s_or_b32 s70, s6, s48
	s_lshl_b64 s[46:47], s[46:47], 12
	s_or_b32 s48, s55, s6
	s_lshl_b32 s49, s35, 3
	v_readlane_b32 s6, v253, 57
	s_add_u32 s46, s46, s6
	s_addc_u32 s47, s47, 0
	s_or_b32 s46, s46, s48
	v_add_u32_e32 v26, s49, v140
	v_mov_b32_e32 v25, s47
	v_or_b32_e32 v24, s46, v100
	v_lshl_add_u32 v27, v26, 1, v143
	v_lshlrev_b64 v[24:25], 7, v[24:25]
	v_add_u32_e32 v28, 32, v27
	v_lshl_add_u64 v[24:25], v[102:103], 0, v[24:25]
	s_waitcnt lgkmcnt(0)
	s_barrier
	global_load_dwordx4 v[80:83], v[24:25], off
	global_load_dwordx4 v[84:87], v[24:25], off offset:64
	v_or_b32_e32 v24, s48, v100
	v_max_i32_e32 v25, 8, v24
	v_add_u32_e32 v25, -8, v25
	v_min_u32_e32 v25, 48, v25
	v_add_u32_e32 v26, s54, v26
	v_sub_u32_e32 v25, v26, v25
	v_lshl_add_u32 v26, s35, 2, v141
	v_add_u32_e32 v29, s49, v100
	v_bitop3_b32 v30, v26, v137, 7 bitop3:0x6c
	v_bitop3_b32 v26, v26, v142, 7 bitop3:0x6c
	s_add_i32 s49, s49, s54
	v_lshlrev_b32_e32 v172, 4, v26
	v_add_u32_e32 v26, s49, v144
	v_sub_u32_e32 v173, v26, v24
	v_and_b32_e32 v26, 64, v207
	v_xor_b32_e32 v24, 16, v207
	v_add_u32_e32 v26, 64, v26
	v_cmp_lt_i32_e32 vcc, v24, v26
	s_add_i32 s66, s66, s69
	s_ashr_i32 s67, s66, 31
	v_cndmask_b32_e32 v24, v207, v24, vcc
	v_lshlrev_b32_e32 v175, 2, v24
	v_xor_b32_e32 v24, 32, v207
	v_cmp_lt_i32_e32 vcc, v24, v26
	s_lshl_b64 s[66:67], s[66:67], 12
	s_ashr_i32 s35, s34, 31
	v_cndmask_b32_e32 v24, v207, v24, vcc
	v_lshlrev_b32_e32 v176, 2, v24
	v_add_u32_e32 v24, 1, v25
	v_cmp_gt_u32_e64 s[48:49], 16, v24
	v_add_u32_e32 v24, 2, v25
	v_cmp_gt_u32_e64 s[50:51], 16, v24
	v_add_u32_e32 v24, 3, v25
	v_cmp_gt_u32_e64 s[52:53], 16, v24
	v_add_u32_e32 v24, 17, v25
	v_cmp_gt_u32_e64 s[56:57], 16, v24
	v_add_u32_e32 v24, 18, v25
	s_movk_i32 s54, 0xffef
	v_cmp_gt_u32_e64 s[58:59], 16, v24
	v_add_u32_e32 v24, 19, v25
	s_or_b32 s66, s66, s70
	s_lshl_b64 s[34:35], s[34:35], 12
	v_cmp_gt_u32_e64 s[46:47], 16, v25
	v_cmp_lt_u32_e64 s[54:55], s54, v25
	v_cmp_gt_u32_e64 s[60:61], 16, v24
	v_lshl_add_u64 v[24:25], s[66:67], 0, v[106:107]
	v_lshlrev_b64 v[24:25], 7, v[24:25]
	s_or_b32 s34, s34, s70
	v_lshl_add_u64 v[124:125], v[104:105], 0, v[24:25]
	v_lshl_add_u64 v[126:127], v[108:109], 0, v[24:25]
	v_lshl_add_u64 v[24:25], s[34:35], 0, v[106:107]
	v_lshlrev_b64 v[24:25], 11, v[24:25]
	v_lshl_or_b32 v24, s69, 7, v24
	v_lshlrev_b32_e32 v171, 4, v30
	v_lshl_add_u32 v174, v29, 7, 0
	s_mov_b32 s80, 0
	v_add_u32_e32 v177, 0, v27
	v_add_u32_e32 v178, 0, v28
	v_mov_b32_e32 v115, v189
	v_mov_b32_e32 v117, v189
	v_mov_b32_e32 v119, v189
	v_mov_b32_e32 v121, v189
	v_mov_b32_e32 v123, v189
	v_lshl_add_u64 v[128:129], v[110:111], 0, v[24:25]
	v_lshl_add_u64 v[130:131], v[112:113], 0, v[24:25]
	s_mov_b64 s[34:35], 0
	v_readlane_b32 s81, v254, 1
	s_mov_b32 s86, s19
	v_readlane_b32 s7, v253, 58
	s_waitcnt vmcnt(0)
.LBB0_470:
	s_waitcnt vmcnt(2)
	v_med3_u32 v24, s80, 1, 57
	s_min_u32 s66, s80, 53
	v_readfirstlane_b32 s67, v24
	s_sub_i32 s69, s66, s67
	s_add_i32 s87, s67, 7
	s_add_i32 s88, s69, 4
	s_cmp_gt_i32 s69, -4
	s_cselect_b64 s[66:67], -1, 0
	s_cmp_lt_i32 s69, -3
	v_cmp_gt_i32_e32 vcc, s88, v145
	s_cbranch_scc1 .LBB0_480
	s_lshl_b32 s69, s87, 13
	s_add_u32 s70, s20, s69
	s_addc_u32 s71, s21, 0
	s_and_saveexec_b64 s[82:83], vcc
	s_cbranch_execz .LBB0_473
	v_lshl_add_u64 v[12:13], s[70:71], 0, v[188:189]
	global_load_dwordx4 v[12:15], v[12:13], off
